# FFN-up GEMM epilogue: the eight per-row-group rsqrt-scale loads issued together instead of load-wait-load
# baseline (speedup 1.0000x reference)
; __device__ __forceinline__ unsigned cvt_pk_bf16(float lo, float hi) { unsigned r; asm volatile("v_cvt_pk_bf16_f32 %0, %1, %2" : "=v"(r) : "v"(lo), "v"(hi)); return r; }
;     __device__ __forceinline__ void operator()(const f32x4 (&acc)[2][2][4][2], const Unit& u, int wr, int wc, int fr, int fq) const {
;     ...
;             for (int m = 0; m < 4; ++m) { bf16_t* rowp = O + (size_t)(row0 + ai * HALF + m * 16) * ldc + col0;
;                 const float rr = fused ? __builtin_amdgcn_rsqf(ssq[row0 + ai * HALF + m * 16] * inv_n + EPS) : 1.f;
; #pragma unroll
;                 for (int bj = 0; bj < 2; ++bj) { const f32x4 v0 = act4(acc[ai][bj][m][0] * rr + bv[bj][0], ACT), v1 = act4(acc[ai][bj][m][1] * rr + bv[bj][1], ACT);
;                     u32x4 w; w.x = cvt_pk_bf16(v0[0], v0[1]); w.y = cvt_pk_bf16(v0[2], v0[3]); w.z = cvt_pk_bf16(v1[0], v1[1]); w.w = cvt_pk_bf16(v1[2], v1[3]);
;                     *(u32x4*)(rowp + bj * 32) = w; } }
.LBB0_1797:
	v_lshl_add_u32 v158, s30, 8, v161
	v_ashrrev_i32_e32 v159, 31, v158
	v_mov_b32_e32 v160, 1.0
	s_and_b64 vcc, exec, s[10:11]
	v_lshl_add_u64 v[156:157], v[158:159], 2, s[16:17]
	v_mov_b32_e32 v162, 1.0
	s_cbranch_vccnz .LBB0_1799
	global_load_dword v162, v[156:157], off
	global_load_dword v193, v[156:157], off offset:64
	global_load_dword v194, v[156:157], off offset:128
	global_load_dword v195, v[156:157], off offset:192
	global_load_dword v196, v[156:157], off offset:512
	global_load_dword v197, v[156:157], off offset:576
	global_load_dword v198, v[156:157], off offset:640
	global_load_dword v199, v[156:157], off offset:704
	s_waitcnt vmcnt(0)
	v_fmamk_f32 v162, v162, 0x3a800000, v189
	v_rsq_f32_e32 v162, v162
.LBB0_1799:
	s_waitcnt vmcnt(0)
	v_pk_fma_f32 v[120:121], v[120:121], v[162:163], v[128:129] op_sel_hi:[1,0,1]
	v_pk_fma_f32 v[122:123], v[122:123], v[162:163], v[130:131] op_sel_hi:[1,0,1]
	v_max_f32_e32 v120, 0, v120
	v_mul_f32_e32 v168, v120, v120
	v_max_f32_e32 v120, 0, v121
	v_lshlrev_b64 v[166:167], 13, v[158:159]
	v_pk_fma_f32 v[124:125], v[124:125], v[162:163], v[136:137] op_sel_hi:[1,0,1]
	v_mul_f32_e32 v169, v120, v120
	v_max_f32_e32 v120, 0, v122
	v_lshl_add_u64 v[166:167], s[14:15], 0, v[166:167]
	v_pk_fma_f32 v[126:127], v[126:127], v[162:163], v[138:139] op_sel_hi:[1,0,1]
	v_max_f32_e32 v124, 0, v124
	v_max_f32_e32 v125, 0, v125
	v_mul_f32_e32 v170, v120, v120
	v_max_f32_e32 v120, 0, v123
	v_pk_fma_f32 v[112:113], v[112:113], v[162:163], v[132:133] op_sel_hi:[1,0,1]
	v_lshl_add_u64 v[166:167], v[154:155], 1, v[166:167]
	v_mul_f32_e32 v124, v124, v124
	v_mul_f32_e32 v125, v125, v125
	v_max_f32_e32 v126, 0, v126
	v_max_f32_e32 v127, 0, v127
	v_mul_f32_e32 v123, v120, v120
	v_cvt_pk_bf16_f32 v120, v124, v125
	v_max_f32_e32 v112, 0, v112
	v_mul_f32_e32 v126, v126, v126
	v_mul_f32_e32 v127, v127, v127
	v_cvt_pk_bf16_f32 v121, v126, v127
	v_cvt_pk_bf16_f32 v122, v168, v169
	v_cvt_pk_bf16_f32 v123, v170, v123
	global_store_dwordx4 v[166:167], v[120:123], off
	v_pk_fma_f32 v[116:117], v[116:117], v[162:163], v[140:141] op_sel_hi:[1,0,1]
	v_pk_fma_f32 v[114:115], v[114:115], v[162:163], v[134:135] op_sel_hi:[1,0,1]
	v_mul_f32_e32 v120, v112, v112
	v_max_f32_e32 v112, 0, v113
	v_max_f32_e32 v116, 0, v116
	v_mul_f32_e32 v121, v112, v112
	v_max_f32_e32 v112, 0, v114
	v_mul_f32_e32 v116, v116, v116
	v_max_f32_e32 v117, 0, v117
	v_mul_f32_e32 v122, v112, v112
	v_max_f32_e32 v112, 0, v115
	v_pk_fma_f32 v[118:119], v[118:119], v[162:163], v[142:143] op_sel_hi:[1,0,1]
	v_mul_f32_e32 v117, v117, v117
	v_mul_f32_e32 v115, v112, v112
	v_cvt_pk_bf16_f32 v112, v116, v117
	v_cndmask_b32_e64 v116, 0, 1, s[34:35]
	v_max_f32_e32 v118, 0, v118
	v_max_f32_e32 v119, 0, v119
	v_cmp_ne_u32_e64 s[10:11], 1, v116
	s_andn2_b64 vcc, exec, s[34:35]
	v_mul_f32_e32 v118, v118, v118
	v_mul_f32_e32 v119, v119, v119
	v_cvt_pk_bf16_f32 v113, v118, v119
	v_cvt_pk_bf16_f32 v114, v120, v121
	v_cvt_pk_bf16_f32 v115, v122, v115
	global_store_dwordx4 v[166:167], v[112:115], off offset:64
	s_cbranch_vccnz .LBB0_1801
	s_nop 2
	v_mov_b32_e32 v112, v193
	v_fmamk_f32 v112, v112, 0x3a800000, v189
	v_rsq_f32_e32 v160, v112
.LBB0_1801:
	s_nop 0
	v_pk_fma_f32 v[104:105], v[104:105], v[160:161], v[128:129] op_sel_hi:[1,0,1]
	v_or_b32_e32 v112, 16, v158
	v_max_f32_e32 v104, 0, v104
	v_ashrrev_i32_e32 v113, 31, v112
	v_pk_fma_f32 v[106:107], v[106:107], v[160:161], v[130:131] op_sel_hi:[1,0,1]
	v_mul_f32_e32 v114, v104, v104
	v_max_f32_e32 v104, 0, v105
	v_lshlrev_b64 v[112:113], 13, v[112:113]
	v_pk_fma_f32 v[108:109], v[108:109], v[160:161], v[136:137] op_sel_hi:[1,0,1]
	v_mul_f32_e32 v115, v104, v104
	v_max_f32_e32 v104, 0, v106
	v_lshl_add_u64 v[112:113], s[14:15], 0, v[112:113]
	v_pk_fma_f32 v[110:111], v[110:111], v[160:161], v[138:139] op_sel_hi:[1,0,1]
	v_max_f32_e32 v108, 0, v108
	v_max_f32_e32 v109, 0, v109
	v_mul_f32_e32 v116, v104, v104
	v_max_f32_e32 v104, 0, v107
	v_pk_fma_f32 v[96:97], v[96:97], v[160:161], v[132:133] op_sel_hi:[1,0,1]
	v_lshl_add_u64 v[112:113], v[154:155], 1, v[112:113]
	v_mul_f32_e32 v108, v108, v108
	v_mul_f32_e32 v109, v109, v109
	v_max_f32_e32 v110, 0, v110
	v_max_f32_e32 v111, 0, v111
	v_mul_f32_e32 v107, v104, v104
	v_cvt_pk_bf16_f32 v104, v108, v109
	v_max_f32_e32 v96, 0, v96
	v_mul_f32_e32 v110, v110, v110
	v_mul_f32_e32 v111, v111, v111
	v_cvt_pk_bf16_f32 v105, v110, v111
	v_cvt_pk_bf16_f32 v106, v114, v115
	v_cvt_pk_bf16_f32 v107, v116, v107
	global_store_dwordx4 v[112:113], v[104:107], off
	v_pk_fma_f32 v[98:99], v[98:99], v[160:161], v[134:135] op_sel_hi:[1,0,1]
	v_pk_fma_f32 v[102:103], v[102:103], v[160:161], v[142:143] op_sel_hi:[1,0,1]
	v_mul_f32_e32 v104, v96, v96
	v_max_f32_e32 v96, 0, v97
	v_pk_fma_f32 v[100:101], v[100:101], v[160:161], v[140:141] op_sel_hi:[1,0,1]
	v_mul_f32_e32 v105, v96, v96
	v_max_f32_e32 v96, 0, v98
	v_max_f32_e32 v100, 0, v100
	v_max_f32_e32 v101, 0, v101
	v_max_f32_e32 v102, 0, v102
	v_max_f32_e32 v103, 0, v103
	v_mul_f32_e32 v106, v96, v96
	v_max_f32_e32 v96, 0, v99
	v_mul_f32_e32 v100, v100, v100
	v_mul_f32_e32 v101, v101, v101
	v_mul_f32_e32 v102, v102, v102
	v_mul_f32_e32 v103, v103, v103
	v_mul_f32_e32 v99, v96, v96
	v_cvt_pk_bf16_f32 v96, v100, v101
	v_cvt_pk_bf16_f32 v97, v102, v103
	v_cvt_pk_bf16_f32 v98, v104, v105
	v_cvt_pk_bf16_f32 v99, v106, v99
	global_store_dwordx4 v[112:113], v[96:99], off offset:64
	s_and_b64 vcc, exec, s[10:11]
	s_nop 0
	v_mov_b32_e32 v96, 1.0
	v_mov_b32_e32 v98, 1.0
	s_cbranch_vccnz .LBB0_1803
	s_nop 2
	v_mov_b32_e32 v97, v194
	v_fmamk_f32 v97, v97, 0x3a800000, v189
	v_rsq_f32_e32 v98, v97
; __device__ __forceinline__ unsigned cvt_pk_bf16(float lo, float hi) { unsigned r; asm volatile("v_cvt_pk_bf16_f32 %0, %1, %2" : "=v"(r) : "v"(lo), "v"(hi)); return r; }
;     __device__ __forceinline__ void operator()(const f32x4 (&acc)[2][2][4][2], const Unit& u, int wr, int wc, int fr, int fq) const {
;     ...
;             for (int m = 0; m < 4; ++m) { bf16_t* rowp = O + (size_t)(row0 + ai * HALF + m * 16) * ldc + col0;
;                 const float rr = fused ? __builtin_amdgcn_rsqf(ssq[row0 + ai * HALF + m * 16] * inv_n + EPS) : 1.f;
; #pragma unroll
;                 for (int bj = 0; bj < 2; ++bj) { const f32x4 v0 = act4(acc[ai][bj][m][0] * rr + bv[bj][0], ACT), v1 = act4(acc[ai][bj][m][1] * rr + bv[bj][1], ACT);
;                     u32x4 w; w.x = cvt_pk_bf16(v0[0], v0[1]); w.y = cvt_pk_bf16(v0[2], v0[3]); w.z = cvt_pk_bf16(v1[0], v1[1]); w.w = cvt_pk_bf16(v1[2], v1[3]);
;                     *(u32x4*)(rowp + bj * 32) = w; } }
.LBB0_1803:
	s_nop 0
	v_pk_fma_f32 v[88:89], v[88:89], v[98:99], v[128:129] op_sel_hi:[1,0,1]
	v_or_b32_e32 v100, 32, v158
	v_max_f32_e32 v88, 0, v88
	v_ashrrev_i32_e32 v101, 31, v100
	v_pk_fma_f32 v[90:91], v[90:91], v[98:99], v[130:131] op_sel_hi:[1,0,1]
	v_mul_f32_e32 v97, v88, v88
	v_max_f32_e32 v88, 0, v89
	v_lshlrev_b64 v[100:101], 13, v[100:101]
	v_pk_fma_f32 v[94:95], v[94:95], v[98:99], v[138:139] op_sel_hi:[1,0,1]
	v_pk_fma_f32 v[92:93], v[92:93], v[98:99], v[136:137] op_sel_hi:[1,0,1]
	v_mul_f32_e32 v99, v88, v88
	v_max_f32_e32 v88, 0, v90
	v_lshl_add_u64 v[100:101], s[14:15], 0, v[100:101]
	v_max_f32_e32 v92, 0, v92
	v_max_f32_e32 v93, 0, v93
	v_mul_f32_e32 v102, v88, v88
	v_max_f32_e32 v88, 0, v91
	v_pk_fma_f32 v[80:81], v[80:81], v[98:99], v[132:133] op_sel_hi:[1,0,1]
	v_lshl_add_u64 v[100:101], v[154:155], 1, v[100:101]
	v_mul_f32_e32 v92, v92, v92
	v_mul_f32_e32 v93, v93, v93
	v_max_f32_e32 v94, 0, v94
	v_max_f32_e32 v95, 0, v95
	v_mul_f32_e32 v91, v88, v88
	v_cvt_pk_bf16_f32 v88, v92, v93
	v_max_f32_e32 v80, 0, v80
	v_mul_f32_e32 v94, v94, v94
	v_mul_f32_e32 v95, v95, v95
	v_cvt_pk_bf16_f32 v89, v94, v95
	v_cvt_pk_bf16_f32 v90, v97, v99
	v_cvt_pk_bf16_f32 v91, v102, v91
	global_store_dwordx4 v[100:101], v[88:91], off
	v_pk_fma_f32 v[82:83], v[82:83], v[98:99], v[134:135] op_sel_hi:[1,0,1]
	v_pk_fma_f32 v[86:87], v[86:87], v[98:99], v[142:143] op_sel_hi:[1,0,1]
	v_mul_f32_e32 v88, v80, v80
	v_max_f32_e32 v80, 0, v81
	v_mul_f32_e32 v89, v80, v80
	v_max_f32_e32 v80, 0, v82
	v_pk_fma_f32 v[84:85], v[84:85], v[98:99], v[140:141] op_sel_hi:[1,0,1]
	v_mul_f32_e32 v90, v80, v80
	v_max_f32_e32 v80, 0, v83
	v_max_f32_e32 v84, 0, v84
	v_max_f32_e32 v85, 0, v85
	v_max_f32_e32 v86, 0, v86
	v_max_f32_e32 v87, 0, v87
	v_mul_f32_e32 v83, v80, v80
	s_and_b64 vcc, exec, s[10:11]
	v_mul_f32_e32 v84, v84, v84
	v_mul_f32_e32 v85, v85, v85
	v_mul_f32_e32 v86, v86, v86
	v_mul_f32_e32 v87, v87, v87
	v_cvt_pk_bf16_f32 v80, v84, v85
	v_cvt_pk_bf16_f32 v81, v86, v87
	v_cvt_pk_bf16_f32 v82, v88, v89
	v_cvt_pk_bf16_f32 v83, v90, v83
	global_store_dwordx4 v[100:101], v[80:83], off offset:64
	s_cbranch_vccnz .LBB0_1805
	s_nop 2
	v_mov_b32_e32 v80, v195
	v_fmamk_f32 v80, v80, 0x3a800000, v189
	v_rsq_f32_e32 v96, v80
.LBB0_1805:
	s_nop 0
	v_pk_fma_f32 v[72:73], v[72:73], v[96:97], v[128:129] op_sel_hi:[1,0,1]
	v_or_b32_e32 v80, 48, v158
	v_max_f32_e32 v72, 0, v72
	v_ashrrev_i32_e32 v81, 31, v80
	v_pk_fma_f32 v[74:75], v[74:75], v[96:97], v[130:131] op_sel_hi:[1,0,1]
	v_mul_f32_e32 v82, v72, v72
	v_max_f32_e32 v72, 0, v73
	v_lshlrev_b64 v[80:81], 13, v[80:81]
	v_pk_fma_f32 v[76:77], v[76:77], v[96:97], v[136:137] op_sel_hi:[1,0,1]
	v_mul_f32_e32 v83, v72, v72
	v_max_f32_e32 v72, 0, v74
	v_lshl_add_u64 v[80:81], s[14:15], 0, v[80:81]
	v_pk_fma_f32 v[78:79], v[78:79], v[96:97], v[138:139] op_sel_hi:[1,0,1]
	v_max_f32_e32 v76, 0, v76
	v_max_f32_e32 v77, 0, v77
	v_mul_f32_e32 v84, v72, v72
	v_max_f32_e32 v72, 0, v75
	v_pk_fma_f32 v[64:65], v[64:65], v[96:97], v[132:133] op_sel_hi:[1,0,1]
	v_lshl_add_u64 v[80:81], v[154:155], 1, v[80:81]
	v_mul_f32_e32 v76, v76, v76
	v_mul_f32_e32 v77, v77, v77
	v_max_f32_e32 v78, 0, v78
	v_max_f32_e32 v79, 0, v79
	v_mul_f32_e32 v75, v72, v72
	v_cvt_pk_bf16_f32 v72, v76, v77
	v_max_f32_e32 v64, 0, v64
	v_mul_f32_e32 v78, v78, v78
	v_mul_f32_e32 v79, v79, v79
	v_cvt_pk_bf16_f32 v73, v78, v79
	v_cvt_pk_bf16_f32 v74, v82, v83
	v_cvt_pk_bf16_f32 v75, v84, v75
	global_store_dwordx4 v[80:81], v[72:75], off
	v_pk_fma_f32 v[66:67], v[66:67], v[96:97], v[134:135] op_sel_hi:[1,0,1]
	v_pk_fma_f32 v[68:69], v[68:69], v[96:97], v[140:141] op_sel_hi:[1,0,1]
	v_mul_f32_e32 v72, v64, v64
	v_max_f32_e32 v64, 0, v65
	v_mul_f32_e32 v73, v64, v64
	v_max_f32_e32 v64, 0, v66
	v_pk_fma_f32 v[70:71], v[70:71], v[96:97], v[142:143] op_sel_hi:[1,0,1]
	v_max_f32_e32 v68, 0, v68
	v_max_f32_e32 v69, 0, v69
	v_mul_f32_e32 v74, v64, v64
	v_max_f32_e32 v64, 0, v67
	v_mul_f32_e32 v68, v68, v68
	v_mul_f32_e32 v69, v69, v69
	v_max_f32_e32 v70, 0, v70
	v_max_f32_e32 v71, 0, v71
	v_mul_f32_e32 v67, v64, v64
	v_cvt_pk_bf16_f32 v64, v68, v69
	v_mul_f32_e32 v70, v70, v70
	v_mul_f32_e32 v71, v71, v71
	v_cvt_pk_bf16_f32 v65, v70, v71
	v_cvt_pk_bf16_f32 v66, v72, v73
	v_cvt_pk_bf16_f32 v67, v74, v67
	global_store_dwordx4 v[80:81], v[64:67], off offset:64
	s_and_b64 vcc, exec, s[10:11]
	v_mov_b32_e32 v68, 1.0
	v_mov_b32_e32 v64, 1.0
	s_cbranch_vccnz .LBB0_1807
	s_nop 2
	v_mov_b32_e32 v65, v196
	v_fmamk_f32 v65, v65, 0x3a800000, v189
	v_rsq_f32_e32 v68, v65
; __device__ __forceinline__ unsigned cvt_pk_bf16(float lo, float hi) { unsigned r; asm volatile("v_cvt_pk_bf16_f32 %0, %1, %2" : "=v"(r) : "v"(lo), "v"(hi)); return r; }
;     __device__ __forceinline__ void operator()(const f32x4 (&acc)[2][2][4][2], const Unit& u, int wr, int wc, int fr, int fq) const {
;     ...
;             for (int m = 0; m < 4; ++m) { bf16_t* rowp = O + (size_t)(row0 + ai * HALF + m * 16) * ldc + col0;
;                 const float rr = fused ? __builtin_amdgcn_rsqf(ssq[row0 + ai * HALF + m * 16] * inv_n + EPS) : 1.f;
; #pragma unroll
;                 for (int bj = 0; bj < 2; ++bj) { const f32x4 v0 = act4(acc[ai][bj][m][0] * rr + bv[bj][0], ACT), v1 = act4(acc[ai][bj][m][1] * rr + bv[bj][1], ACT);
;                     u32x4 w; w.x = cvt_pk_bf16(v0[0], v0[1]); w.y = cvt_pk_bf16(v0[2], v0[3]); w.z = cvt_pk_bf16(v1[0], v1[1]); w.w = cvt_pk_bf16(v1[2], v1[3]);
;                     *(u32x4*)(rowp + bj * 32) = w; } }
.LBB0_1807:
	s_nop 0
	v_pk_fma_f32 v[56:57], v[56:57], v[68:69], v[128:129] op_sel_hi:[1,0,1]
	v_lshlrev_b64 v[66:67], 13, v[158:159]
	v_max_f32_e32 v56, 0, v56
	v_pk_fma_f32 v[60:61], v[60:61], v[68:69], v[136:137] op_sel_hi:[1,0,1]
	v_pk_fma_f32 v[58:59], v[58:59], v[68:69], v[130:131] op_sel_hi:[1,0,1]
	v_mul_f32_e32 v65, v56, v56
	v_max_f32_e32 v56, 0, v57
	v_lshl_add_u64 v[66:67], s[14:15], 0, v[66:67]
	v_pk_fma_f32 v[62:63], v[62:63], v[68:69], v[138:139] op_sel_hi:[1,0,1]
	v_max_f32_e32 v60, 0, v60
	v_mul_f32_e32 v69, v56, v56
	v_max_f32_e32 v56, 0, v58
	v_lshl_add_u64 v[66:67], v[154:155], 1, v[66:67]
	v_mul_f32_e32 v60, v60, v60
	v_max_f32_e32 v61, 0, v61
	v_mul_f32_e32 v72, v56, v56
	v_max_f32_e32 v56, 0, v59
	s_mov_b32 s23, 0x100000
	v_mul_f32_e32 v61, v61, v61
	v_mul_f32_e32 v59, v56, v56
	v_cvt_pk_bf16_f32 v56, v60, v61
	v_add_co_u32_e32 v60, vcc, s23, v66
	v_pk_fma_f32 v[48:49], v[48:49], v[68:69], v[132:133] op_sel_hi:[1,0,1]
	v_max_f32_e32 v62, 0, v62
	v_max_f32_e32 v63, 0, v63
	v_addc_co_u32_e32 v61, vcc, 0, v67, vcc
	v_max_f32_e32 v48, 0, v48
	v_mul_f32_e32 v62, v62, v62
	v_mul_f32_e32 v63, v63, v63
	v_cvt_pk_bf16_f32 v57, v62, v63
	v_cvt_pk_bf16_f32 v58, v65, v69
	v_cvt_pk_bf16_f32 v59, v72, v59
	global_store_dwordx4 v[60:61], v[56:59], off
	v_pk_fma_f32 v[50:51], v[50:51], v[68:69], v[134:135] op_sel_hi:[1,0,1]
	s_mov_b64 s[34:35], 0x100000
	v_mul_f32_e32 v56, v48, v48
	v_max_f32_e32 v48, 0, v49
	v_mul_f32_e32 v57, v48, v48
	v_max_f32_e32 v48, 0, v50
	v_pk_fma_f32 v[54:55], v[54:55], v[68:69], v[142:143] op_sel_hi:[1,0,1]
	v_pk_fma_f32 v[52:53], v[52:53], v[68:69], v[140:141] op_sel_hi:[1,0,1]
	v_mul_f32_e32 v58, v48, v48
	v_max_f32_e32 v48, 0, v51
	v_lshl_add_u64 v[70:71], v[66:67], 0, s[34:35]
	v_max_f32_e32 v52, 0, v52
	v_max_f32_e32 v53, 0, v53
	v_max_f32_e32 v54, 0, v54
	v_max_f32_e32 v55, 0, v55
	v_mul_f32_e32 v51, v48, v48
	s_and_b64 vcc, exec, s[10:11]
	v_mul_f32_e32 v52, v52, v52
	v_mul_f32_e32 v53, v53, v53
	v_mul_f32_e32 v54, v54, v54
	v_mul_f32_e32 v55, v55, v55
	v_cvt_pk_bf16_f32 v48, v52, v53
	v_cvt_pk_bf16_f32 v49, v54, v55
	v_cvt_pk_bf16_f32 v50, v56, v57
	v_cvt_pk_bf16_f32 v51, v58, v51
	global_store_dwordx4 v[70:71], v[48:51], off offset:64
	s_cbranch_vccnz .LBB0_1809
	s_nop 2
	v_mov_b32_e32 v48, v197
	v_fmamk_f32 v48, v48, 0x3a800000, v189
	v_rsq_f32_e32 v64, v48
.LBB0_1809:
	s_nop 0
	v_pk_fma_f32 v[40:41], v[40:41], v[64:65], v[128:129] op_sel_hi:[1,0,1]
	v_pk_fma_f32 v[44:45], v[44:45], v[64:65], v[136:137] op_sel_hi:[1,0,1]
	v_max_f32_e32 v40, 0, v40
	v_pk_fma_f32 v[42:43], v[42:43], v[64:65], v[130:131] op_sel_hi:[1,0,1]
	v_mul_f32_e32 v50, v40, v40
	v_max_f32_e32 v40, 0, v41
	v_max_f32_e32 v44, 0, v44
	v_mul_f32_e32 v51, v40, v40
	v_max_f32_e32 v40, 0, v42
	v_mul_f32_e32 v44, v44, v44
	v_max_f32_e32 v45, 0, v45
	v_mul_f32_e32 v52, v40, v40
	v_max_f32_e32 v40, 0, v43
	s_mov_b32 s23, 0x120000
	v_pk_fma_f32 v[46:47], v[46:47], v[64:65], v[138:139] op_sel_hi:[1,0,1]
	v_mul_f32_e32 v45, v45, v45
	v_mul_f32_e32 v43, v40, v40
	v_cvt_pk_bf16_f32 v40, v44, v45
	v_add_co_u32_e32 v44, vcc, s23, v66
	v_pk_fma_f32 v[32:33], v[32:33], v[64:65], v[132:133] op_sel_hi:[1,0,1]
	v_max_f32_e32 v46, 0, v46
	v_max_f32_e32 v47, 0, v47
	v_addc_co_u32_e32 v45, vcc, 0, v67, vcc
	v_max_f32_e32 v32, 0, v32
	v_mul_f32_e32 v46, v46, v46
	v_mul_f32_e32 v47, v47, v47
	v_cvt_pk_bf16_f32 v41, v46, v47
	v_cvt_pk_bf16_f32 v42, v50, v51
	v_cvt_pk_bf16_f32 v43, v52, v43
	global_store_dwordx4 v[44:45], v[40:43], off
	v_pk_fma_f32 v[34:35], v[34:35], v[64:65], v[134:135] op_sel_hi:[1,0,1]
	v_pk_fma_f32 v[36:37], v[36:37], v[64:65], v[140:141] op_sel_hi:[1,0,1]
	v_mul_f32_e32 v40, v32, v32
	v_max_f32_e32 v32, 0, v33
	v_mul_f32_e32 v41, v32, v32
	v_max_f32_e32 v32, 0, v34
	s_mov_b64 s[34:35], 0x120000
	v_pk_fma_f32 v[38:39], v[38:39], v[64:65], v[142:143] op_sel_hi:[1,0,1]
	v_max_f32_e32 v36, 0, v36
	v_max_f32_e32 v37, 0, v37
	v_mul_f32_e32 v42, v32, v32
	v_max_f32_e32 v32, 0, v35
	v_lshl_add_u64 v[48:49], v[66:67], 0, s[34:35]
	v_mul_f32_e32 v36, v36, v36
	v_mul_f32_e32 v37, v37, v37
	v_max_f32_e32 v38, 0, v38
	v_max_f32_e32 v39, 0, v39
	v_mul_f32_e32 v35, v32, v32
	v_cvt_pk_bf16_f32 v32, v36, v37
	v_mul_f32_e32 v38, v38, v38
	v_mul_f32_e32 v39, v39, v39
	v_cvt_pk_bf16_f32 v33, v38, v39
	v_cvt_pk_bf16_f32 v34, v40, v41
	v_cvt_pk_bf16_f32 v35, v42, v35
	global_store_dwordx4 v[48:49], v[32:35], off offset:64
	s_and_b64 vcc, exec, s[10:11]
	v_mov_b32_e32 v36, 1.0
	v_mov_b32_e32 v32, 1.0
	s_cbranch_vccnz .LBB0_1811
	s_nop 2
	v_mov_b32_e32 v33, v198
	v_fmamk_f32 v33, v33, 0x3a800000, v189
	v_rsq_f32_e32 v36, v33
.LBB0_1811:
	s_nop 0
	v_pk_fma_f32 v[24:25], v[24:25], v[36:37], v[128:129] op_sel_hi:[1,0,1]
	v_lshlrev_b64 v[34:35], 13, v[158:159]
	v_max_f32_e32 v24, 0, v24
	v_pk_fma_f32 v[28:29], v[28:29], v[36:37], v[136:137] op_sel_hi:[1,0,1]
	v_pk_fma_f32 v[26:27], v[26:27], v[36:37], v[130:131] op_sel_hi:[1,0,1]
	v_mul_f32_e32 v33, v24, v24
	v_max_f32_e32 v24, 0, v25
	v_lshl_add_u64 v[34:35], s[14:15], 0, v[34:35]
	v_pk_fma_f32 v[30:31], v[30:31], v[36:37], v[138:139] op_sel_hi:[1,0,1]
	v_max_f32_e32 v28, 0, v28
	v_mul_f32_e32 v37, v24, v24
	v_max_f32_e32 v24, 0, v26
	v_lshl_add_u64 v[34:35], v[154:155], 1, v[34:35]
	v_mul_f32_e32 v28, v28, v28
	v_max_f32_e32 v29, 0, v29
	v_mul_f32_e32 v40, v24, v24
	v_max_f32_e32 v24, 0, v27
	s_mov_b32 s23, 0x140000
	v_mul_f32_e32 v29, v29, v29
	v_mul_f32_e32 v27, v24, v24
	v_cvt_pk_bf16_f32 v24, v28, v29
	v_add_co_u32_e32 v28, vcc, s23, v34
	v_pk_fma_f32 v[16:17], v[16:17], v[36:37], v[132:133] op_sel_hi:[1,0,1]
	v_max_f32_e32 v30, 0, v30
	v_max_f32_e32 v31, 0, v31
	v_addc_co_u32_e32 v29, vcc, 0, v35, vcc
	v_max_f32_e32 v16, 0, v16
	v_mul_f32_e32 v30, v30, v30
	v_mul_f32_e32 v31, v31, v31
	v_cvt_pk_bf16_f32 v25, v30, v31
	v_cvt_pk_bf16_f32 v26, v33, v37
	v_cvt_pk_bf16_f32 v27, v40, v27
	global_store_dwordx4 v[28:29], v[24:27], off
	v_pk_fma_f32 v[18:19], v[18:19], v[36:37], v[134:135] op_sel_hi:[1,0,1]
	s_mov_b64 s[34:35], 0x140000
	v_mul_f32_e32 v24, v16, v16
	v_max_f32_e32 v16, 0, v17
	v_mul_f32_e32 v25, v16, v16
	v_max_f32_e32 v16, 0, v18
	v_pk_fma_f32 v[22:23], v[22:23], v[36:37], v[142:143] op_sel_hi:[1,0,1]
	v_pk_fma_f32 v[20:21], v[20:21], v[36:37], v[140:141] op_sel_hi:[1,0,1]
	v_mul_f32_e32 v26, v16, v16
	v_max_f32_e32 v16, 0, v19
	v_lshl_add_u64 v[38:39], v[34:35], 0, s[34:35]
	v_max_f32_e32 v20, 0, v20
	v_max_f32_e32 v21, 0, v21
	v_max_f32_e32 v22, 0, v22
	v_max_f32_e32 v23, 0, v23
	v_mul_f32_e32 v19, v16, v16
	s_and_b64 vcc, exec, s[10:11]
	v_mul_f32_e32 v20, v20, v20
	v_mul_f32_e32 v21, v21, v21
	v_mul_f32_e32 v22, v22, v22
	v_mul_f32_e32 v23, v23, v23
	v_cvt_pk_bf16_f32 v16, v20, v21
	v_cvt_pk_bf16_f32 v17, v22, v23
	v_cvt_pk_bf16_f32 v18, v24, v25
	v_cvt_pk_bf16_f32 v19, v26, v19
	global_store_dwordx4 v[38:39], v[16:19], off offset:64
	s_cbranch_vccnz .LBB0_1813
	s_nop 2
	v_mov_b32_e32 v16, v199
	v_fmamk_f32 v16, v16, 0x3a800000, v189
	v_rsq_f32_e32 v32, v16
